# p0b weight-conversion tail: chunk dequeue issued one chunk ahead
# speedup vs baseline: 1.0091x; 1.0064x over previous
.LBB0_357:
	v_mov_b32_e32 v1, v152
	s_lshl_b32 s0, s91, 14
	s_add_i32 s0, s0, 0
	v_ashrrev_i32_e32 v0, 5, v1
	v_and_b32_e32 v34, 31, v1
	v_ashrrev_i32_e32 v49, 3, v1
	v_lshlrev_b32_e32 v1, 3, v1
	s_add_u32 s6, s24, 0x74700
	v_and_b32_e32 v6, 56, v1
	s_addc_u32 s7, s25, 0
	s_add_i32 s3, s91, 0x500
	v_lshlrev_b32_e32 v2, 2, v34
	v_mul_u32_u24_e32 v1, 0x84, v6
	v_lshlrev_b32_e32 v5, 2, v49
	v_add_u32_e32 v4, s0, v2
	v_add3_u32 v51, s0, v1, v5
	s_add_u32 s0, s24, 0x2600000
	v_writelane_b32 v254, s0, 41
	s_addc_u32 s0, s25, 0
	v_writelane_b32 v254, s0, 43
	s_add_u32 s0, s24, 0x1000000
	v_writelane_b32 v254, s0, 44
	s_addc_u32 s0, s25, 0
	v_writelane_b32 v254, s0, 46
	s_add_u32 s8, s24, 0xe00000
	v_mov_b32_e32 v3, 0
	v_readlane_b32 s36, v254, 21
	s_addc_u32 s9, s25, 0
	v_readlane_b32 s37, v254, 22
	v_readlane_b32 s38, v254, 23
	v_readlane_b32 s39, v254, 24
	v_readlane_b32 s40, v254, 25
	v_readlane_b32 s41, v254, 26
	v_readlane_b32 s42, v254, 27
	v_readlane_b32 s43, v254, 28
	v_readlane_b32 s44, v254, 29
	v_readlane_b32 s45, v254, 30
	v_readlane_b32 s46, v254, 31
	v_readlane_b32 s47, v254, 32
	v_readlane_b32 s48, v254, 33
	v_readlane_b32 s49, v254, 34
	v_readlane_b32 s50, v254, 35
	v_readlane_b32 s51, v254, 36
	v_lshlrev_b32_e32 v18, 1, v6
	v_mov_b32_e32 v19, v3
	v_writelane_b32 v254, s8, 47
	v_add_u32_e32 v20, 4, v0
	v_add_u32_e32 v22, 8, v0
	v_writelane_b32 v254, s9, 48
	v_lshl_add_u64 v[10:11], s[8:9], 0, v[18:19]
	s_add_u32 s8, s24, 0x800000
	s_addc_u32 s9, s25, 0
	s_add_u32 s94, s24, 0x600000
	v_writelane_b32 v254, s8, 49
	s_addc_u32 s95, s25, 0
	v_add_u32_e32 v24, 12, v0
	v_add_u32_e32 v26, 16, v0
	v_add_u32_e32 v28, 20, v0
	v_add_u32_e32 v30, 24, v0
	v_add_u32_e32 v32, 28, v0
	s_add_i32 s17, 0, 0x20080
	s_mov_b32 s1, 0
	s_movk_i32 s16, 0x84
	v_add_u32_e32 v52, 8, v49
	v_add_u32_e32 v53, 16, v49
	v_add_u32_e32 v54, 24, v49
	v_lshl_add_u64 v[8:9], s[46:47], 0, v[2:3]
	v_lshl_add_u64 v[12:13], s[42:43], 0, v[2:3]
	v_writelane_b32 v254, s9, 50
	v_lshl_add_u64 v[14:15], s[8:9], 0, v[18:19]
	v_lshl_add_u64 v[16:17], s[40:41], 0, v[2:3]
	v_lshl_add_u64 v[18:19], s[94:95], 0, v[18:19]
	v_mov_b32_e32 v1, v0
	v_mov_b32_e32 v5, v20
	v_mov_b32_e32 v7, v22
	v_mov_b32_e32 v21, v24
	v_mov_b32_e32 v23, v26
	v_mov_b32_e32 v25, v28
	v_mov_b32_e32 v27, v30
	v_mov_b32_e32 v29, v32
	v_mov_b32_e32 v55, s17
	s_movk_i32 s28, 0x55f
	s_movk_i32 s29, 0x1600
	s_movk_i32 s40, 0x2c00
	s_movk_i32 s41, 0x3000
	v_lshlrev_b32_e32 v2, 2, v34
	v_readlane_b32 s98, v254, 39
	v_readlane_b32 s99, v254, 40
	s_mov_b64 vcc, exec
	s_and_b64 exec, exec, s[98:99]
	v_mov_b32_e32 v253, 1
	global_atomic_add v253, v3, v253, s[6:7] sc0
	s_mov_b64 exec, vcc
	s_mov_b32 s99, 0
	s_branch .LBB0_360

.LBB0_360:
	s_barrier
	s_mov_b64 s[14:15], exec
	v_readlane_b32 s8, v254, 39
	v_readlane_b32 s9, v254, 40
	s_and_b64 s[8:9], s[14:15], s[8:9]
	s_mov_b64 exec, s[8:9]
	s_cbranch_execz .LBB0_364
	s_mov_b64 s[38:39], exec
	v_mbcnt_lo_u32_b32 v31, s38, 0
	v_mbcnt_hi_u32_b32 v31, s39, v31
	v_cmp_eq_u32_e32 vcc, 0, v31
	s_and_saveexec_b64 s[36:37], vcc
	s_cbranch_execz .LBB0_363
	s_bcnt1_i32_b64 s0, s[38:39]
	s_waitcnt vmcnt(0)
	v_mov_b32_e32 v33, v253
	v_mov_b32_e32 v253, s0
	global_atomic_add v253, v3, v253, s[6:7] sc0
.LBB0_363:
	s_or_b64 exec, exec, s[36:37]
	s_nop 0
	v_readfirstlane_b32 s0, v33
	v_mov_b32_e32 v33, s17
	s_nop 0
	v_add_u32_e32 v31, s0, v31
	ds_write_b32 v33, v31
